# adds: state-scan phase prefetches the 32 normaliser increments instead of 32 serialized load+store-drain steps
# speedup vs baseline: 1.0352x; 1.0150x over previous
.LBB0_144:
	v_ashrrev_i32_e32 v28, 14, v35
	v_ashrrev_i32_e32 v29, 31, v28
	v_and_b32_e32 v66, 0x3fff, v35
	v_ashrrev_i32_e32 v30, 12, v35
	s_waitcnt lgkmcnt(0)
	v_lshlrev_b64 v[0:1], 21, v[28:29]
	v_lshl_add_u64 v[0:1], s[60:61], 0, v[0:1]
	v_lshlrev_b32_e32 v156, 2, v66
	v_ashrrev_i32_e32 v31, 31, v30
	v_readlane_b32 s8, v251, 61
	v_and_b32_e32 v2, 0xfff, v35
	v_lshl_add_u64 v[24:25], v[0:1], 0, v[156:157]
	v_lshlrev_b64 v[0:1], 19, v[30:31]
	v_readlane_b32 s9, v251, 62
	v_lshlrev_b32_e32 v32, 2, v2
	v_mov_b32_e32 v33, v157
	v_lshl_add_u64 v[0:1], s[8:9], 0, v[0:1]
	s_mov_b32 s9, 0x10000
	v_lshl_add_u64 v[26:27], v[0:1], 0, v[32:33]
	v_cmp_gt_u32_e64 s[42:43], 64, v66
	v_readlane_b32 s16, v251, 59
	v_readlane_b32 s17, v251, 60
	s_mov_b64 s[18:19], 0x1000
	s_and_saveexec_b64 s[14:15], s[42:43]
	s_cbranch_execz .Lscan_nopf
	v_lshlrev_b32_e32 v144, 3, v66
	v_lshl_add_u32 v144, v28, 14, v144
	v_mov_b32_e32 v145, 0
	v_lshl_add_u64 v[144:145], s[16:17], 0, v[144:145]
	global_load_dwordx2 v[80:81], v[144:145], off
	global_load_dwordx2 v[82:83], v[144:145], off offset:512
	global_load_dwordx2 v[84:85], v[144:145], off offset:1024
	global_load_dwordx2 v[86:87], v[144:145], off offset:1536
	global_load_dwordx2 v[88:89], v[144:145], off offset:2048
	global_load_dwordx2 v[90:91], v[144:145], off offset:2560
	global_load_dwordx2 v[92:93], v[144:145], off offset:3072
	global_load_dwordx2 v[94:95], v[144:145], off offset:3584
	v_lshl_add_u64 v[144:145], v[144:145], 0, s[18:19]
	global_load_dwordx2 v[96:97], v[144:145], off
	global_load_dwordx2 v[98:99], v[144:145], off offset:512
	global_load_dwordx2 v[100:101], v[144:145], off offset:1024
	global_load_dwordx2 v[102:103], v[144:145], off offset:1536
	global_load_dwordx2 v[104:105], v[144:145], off offset:2048
	global_load_dwordx2 v[106:107], v[144:145], off offset:2560
	global_load_dwordx2 v[108:109], v[144:145], off offset:3072
	global_load_dwordx2 v[110:111], v[144:145], off offset:3584
	v_lshl_add_u64 v[144:145], v[144:145], 0, s[18:19]
	global_load_dwordx2 v[112:113], v[144:145], off
	global_load_dwordx2 v[114:115], v[144:145], off offset:512
	global_load_dwordx2 v[116:117], v[144:145], off offset:1024
	global_load_dwordx2 v[118:119], v[144:145], off offset:1536
	global_load_dwordx2 v[120:121], v[144:145], off offset:2048
	global_load_dwordx2 v[122:123], v[144:145], off offset:2560
	global_load_dwordx2 v[124:125], v[144:145], off offset:3072
	global_load_dwordx2 v[126:127], v[144:145], off offset:3584
	v_lshl_add_u64 v[144:145], v[144:145], 0, s[18:19]
	global_load_dwordx2 v[128:129], v[144:145], off
	global_load_dwordx2 v[130:131], v[144:145], off offset:512
	global_load_dwordx2 v[132:133], v[144:145], off offset:1024
	global_load_dwordx2 v[134:135], v[144:145], off offset:1536
	global_load_dwordx2 v[136:137], v[144:145], off offset:2048
	global_load_dwordx2 v[138:139], v[144:145], off offset:2560
	global_load_dwordx2 v[140:141], v[144:145], off offset:3072
	global_load_dwordx2 v[142:143], v[144:145], off offset:3584
.Lscan_nopf:
	s_or_b64 exec, exec, s[14:15]
	v_add_co_u32_e32 v0, vcc, s9, v24
	s_movk_i32 s8, 0x4000
	s_nop 0
	v_addc_co_u32_e32 v1, vcc, 0, v25, vcc
	global_load_dword v41, v[24:25], off
	global_load_dword v42, v[26:27], off
	global_load_dword v43, v[0:1], off
	v_add_co_u32_e32 v0, vcc, s8, v26
	s_mov_b32 s10, 0x20000
	s_nop 0
	v_addc_co_u32_e32 v1, vcc, 0, v27, vcc
	global_load_dword v44, v[0:1], off
	v_add_co_u32_e32 v0, vcc, s10, v24
	s_mov_b32 s8, 0x8000
	s_nop 0
	v_addc_co_u32_e32 v1, vcc, 0, v25, vcc
	global_load_dword v45, v[0:1], off
	v_add_co_u32_e32 v0, vcc, s8, v26
	s_mov_b32 s11, 0x30000
	s_nop 0
	v_addc_co_u32_e32 v1, vcc, 0, v27, vcc
	global_load_dword v46, v[0:1], off
	v_add_co_u32_e32 v0, vcc, s11, v24
	s_mov_b32 s8, 0xc000
	s_nop 0
	v_addc_co_u32_e32 v1, vcc, 0, v25, vcc
	global_load_dword v47, v[0:1], off
	v_add_co_u32_e32 v0, vcc, s8, v26
	s_mov_b32 s8, 0x40000
	s_nop 0
	v_addc_co_u32_e32 v1, vcc, 0, v27, vcc
	global_load_dword v48, v[0:1], off
	v_add_co_u32_e32 v0, vcc, s8, v24
	s_mov_b32 s8, 0x50000
	s_nop 0
	v_addc_co_u32_e32 v1, vcc, 0, v25, vcc
	global_load_dword v49, v[0:1], off
	v_add_co_u32_e32 v0, vcc, s9, v26
	s_nop 1
	v_addc_co_u32_e32 v1, vcc, 0, v27, vcc
	global_load_dword v50, v[0:1], off
	v_add_co_u32_e32 v0, vcc, s8, v24
	s_mov_b32 s8, 0x14000
	s_nop 0
	v_addc_co_u32_e32 v1, vcc, 0, v25, vcc
	global_load_dword v51, v[0:1], off
	v_add_co_u32_e32 v0, vcc, s8, v26
	s_mov_b32 s8, 0x60000
	s_nop 0
	v_addc_co_u32_e32 v1, vcc, 0, v27, vcc
	global_load_dword v52, v[0:1], off
	v_add_co_u32_e32 v0, vcc, s8, v24
	s_mov_b32 s8, 0x18000
	s_nop 0
	v_addc_co_u32_e32 v1, vcc, 0, v25, vcc
	global_load_dword v53, v[0:1], off
	v_add_co_u32_e32 v0, vcc, s8, v26
	s_mov_b32 s8, 0x70000
	s_nop 0
	v_addc_co_u32_e32 v1, vcc, 0, v27, vcc
	global_load_dword v54, v[0:1], off
	v_add_co_u32_e32 v0, vcc, s8, v24
	s_mov_b32 s8, 0x1c000
	s_nop 0
	v_addc_co_u32_e32 v1, vcc, 0, v25, vcc
	global_load_dword v55, v[0:1], off
	v_add_co_u32_e32 v0, vcc, s8, v26
	s_mov_b32 s8, 0x80000
	s_nop 0
	v_addc_co_u32_e32 v1, vcc, 0, v27, vcc
	global_load_dword v56, v[0:1], off
	v_add_co_u32_e32 v0, vcc, s8, v24
	s_mov_b32 s8, 0x90000
	s_nop 0
	v_addc_co_u32_e32 v1, vcc, 0, v25, vcc
	global_load_dword v57, v[0:1], off
	v_add_co_u32_e32 v0, vcc, s10, v26
	s_nop 1
	v_addc_co_u32_e32 v1, vcc, 0, v27, vcc
	global_load_dword v58, v[0:1], off
	v_add_co_u32_e32 v0, vcc, s8, v24
	s_mov_b32 s8, 0x24000
	s_nop 0
	v_addc_co_u32_e32 v1, vcc, 0, v25, vcc
	global_load_dword v59, v[0:1], off
	v_add_co_u32_e32 v0, vcc, s8, v26
	s_mov_b32 s8, 0xa0000
	s_nop 0
	v_addc_co_u32_e32 v1, vcc, 0, v27, vcc
	global_load_dword v60, v[0:1], off
	v_add_co_u32_e32 v0, vcc, s8, v24
	s_mov_b32 s8, 0x28000
	s_nop 0
	v_addc_co_u32_e32 v1, vcc, 0, v25, vcc
	global_load_dword v61, v[0:1], off
	v_add_co_u32_e32 v0, vcc, s8, v26
	s_mov_b32 s8, 0xb0000
	s_nop 0
	v_addc_co_u32_e32 v1, vcc, 0, v27, vcc
	global_load_dword v62, v[0:1], off
	v_add_co_u32_e32 v0, vcc, s8, v24
	s_mov_b32 s8, 0x2c000
	s_nop 0
	v_addc_co_u32_e32 v1, vcc, 0, v25, vcc
	global_load_dword v63, v[0:1], off
	v_add_co_u32_e32 v0, vcc, s8, v26
	s_mov_b32 s8, 0xc0000
	s_nop 0
	v_addc_co_u32_e32 v1, vcc, 0, v27, vcc
	global_load_dword v64, v[0:1], off
	v_add_co_u32_e32 v0, vcc, s8, v24
	s_mov_b32 s8, 0xd0000
	s_nop 0
	v_addc_co_u32_e32 v1, vcc, 0, v25, vcc
	global_load_dword v12, v[0:1], off
	v_add_co_u32_e32 v0, vcc, s11, v26
	s_nop 1
	v_addc_co_u32_e32 v1, vcc, 0, v27, vcc
	global_load_dword v14, v[0:1], off
	v_add_co_u32_e32 v0, vcc, s8, v24
	s_mov_b32 s8, 0x34000
	s_nop 0
	v_addc_co_u32_e32 v1, vcc, 0, v25, vcc
	global_load_dword v13, v[0:1], off
	v_add_co_u32_e32 v0, vcc, s8, v26
	s_mov_b32 s8, 0xe0000
	s_nop 0
	v_addc_co_u32_e32 v1, vcc, 0, v27, vcc
	global_load_dword v15, v[0:1], off
	v_add_co_u32_e32 v0, vcc, s8, v24
	s_mov_b32 s8, 0x38000
	s_nop 0
	v_addc_co_u32_e32 v1, vcc, 0, v25, vcc
	global_load_dword v16, v[0:1], off
	v_add_co_u32_e32 v0, vcc, s8, v26
	s_nop 1
	v_addc_co_u32_e32 v1, vcc, 0, v27, vcc
	global_load_dword v18, v[0:1], off
	v_add_co_u32_e32 v0, vcc, 0xf0000, v24
	s_nop 1
	v_addc_co_u32_e32 v1, vcc, 0, v25, vcc
	global_load_dword v17, v[0:1], off
	v_add_co_u32_e32 v0, vcc, 0x3c000, v26
	s_nop 1
	v_addc_co_u32_e32 v1, vcc, 0, v27, vcc
	global_load_dword v19, v[0:1], off
	s_waitcnt vmcnt(0)
	s_barrier
	s_and_saveexec_b64 s[8:9], s[38:39]
	s_cbranch_execz .LBB0_146
	v_lshlrev_b32_e32 v2, 5, v28
	v_add_u32_e32 v0, v36, v2
	v_ashrrev_i32_e32 v1, 31, v0
	v_lshl_add_u64 v[0:1], v[0:1], 2, s[70:71]
	global_load_dword v3, v[0:1], off
	v_add_u32_e32 v0, v38, v2
	v_ashrrev_i32_e32 v1, 31, v0
	v_lshl_add_u64 v[0:1], v[0:1], 2, s[70:71]
	global_load_dword v0, v[0:1], off
	s_waitcnt vmcnt(0)
	ds_write_b32 v37, v0 offset:512
	v_lshl_add_u32 v0, v30, 5, v39
	v_ashrrev_i32_e32 v1, 31, v0
	v_lshl_add_u64 v[0:1], v[0:1], 2, s[70:71]
	global_load_dword v0, v[0:1], off
	s_waitcnt vmcnt(0)
	v_mul_f32_e32 v0, 0x3fb8aa3b, v0
	v_exp_f32_e32 v0, v0
	ds_write2_b32 v37, v0, v3 offset0:64 offset1:96

.LBB0_152:
	s_and_b64 vcc, exec, s[34:35]
	s_cbranch_vccnz .LBB0_154
	v_mov_b32_e32 v80, v112
	v_mov_b32_e32 v81, v113
	v_mov_b32_e32 v82, v114
	v_mov_b32_e32 v83, v115
	v_mov_b32_e32 v84, v116
	v_mov_b32_e32 v85, v117
	v_mov_b32_e32 v86, v118
	v_mov_b32_e32 v87, v119
	v_mov_b32_e32 v88, v120
	v_mov_b32_e32 v89, v121
	v_mov_b32_e32 v90, v122
	v_mov_b32_e32 v91, v123
	v_mov_b32_e32 v92, v124
	v_mov_b32_e32 v93, v125
	v_mov_b32_e32 v94, v126
	v_mov_b32_e32 v95, v127
	v_mov_b32_e32 v96, v128
	v_mov_b32_e32 v97, v129
	v_mov_b32_e32 v98, v130
	v_mov_b32_e32 v99, v131
	v_mov_b32_e32 v100, v132
	v_mov_b32_e32 v101, v133
	v_mov_b32_e32 v102, v134
	v_mov_b32_e32 v103, v135
	v_mov_b32_e32 v104, v136
	v_mov_b32_e32 v105, v137
	v_mov_b32_e32 v106, v138
	v_mov_b32_e32 v107, v139
	v_mov_b32_e32 v108, v140
	v_mov_b32_e32 v109, v141
	v_mov_b32_e32 v110, v142
	v_mov_b32_e32 v111, v143
	s_mov_b32 s49, s29
	s_lshl_b64 s[10:11], s[48:49], 16
	v_lshl_add_u64 v[12:13], v[24:25], 0, s[10:11]
	s_lshl_b64 s[8:9], s[48:49], 14
	s_or_b32 s28, s48, 1
	global_load_dword v41, v[12:13], off
	v_lshl_add_u64 v[12:13], v[26:27], 0, s[8:9]
	s_lshl_b64 s[12:13], s[28:29], 16
	global_load_dword v42, v[12:13], off
	v_lshl_add_u64 v[12:13], v[24:25], 0, s[12:13]
	s_lshl_b64 s[12:13], s[28:29], 14
	s_or_b32 s28, s48, 2
	global_load_dword v43, v[12:13], off
	v_lshl_add_u64 v[12:13], v[26:27], 0, s[12:13]
	s_lshl_b64 s[12:13], s[28:29], 16
	global_load_dword v44, v[12:13], off
	v_lshl_add_u64 v[12:13], v[24:25], 0, s[12:13]
	s_lshl_b64 s[12:13], s[28:29], 14
	s_or_b32 s28, s48, 3
	global_load_dword v45, v[12:13], off
	v_lshl_add_u64 v[12:13], v[26:27], 0, s[12:13]
	s_lshl_b64 s[12:13], s[28:29], 16
	global_load_dword v46, v[12:13], off
	v_lshl_add_u64 v[12:13], v[24:25], 0, s[12:13]
	s_lshl_b64 s[12:13], s[28:29], 14
	s_or_b32 s28, s48, 4
	global_load_dword v47, v[12:13], off
	v_lshl_add_u64 v[12:13], v[26:27], 0, s[12:13]
	s_lshl_b64 s[12:13], s[28:29], 16
	global_load_dword v48, v[12:13], off
	v_lshl_add_u64 v[12:13], v[24:25], 0, s[12:13]
	s_lshl_b64 s[12:13], s[28:29], 14
	s_or_b32 s28, s48, 5
	global_load_dword v49, v[12:13], off
	v_lshl_add_u64 v[12:13], v[26:27], 0, s[12:13]
	s_lshl_b64 s[12:13], s[28:29], 16
	global_load_dword v50, v[12:13], off
	v_lshl_add_u64 v[12:13], v[24:25], 0, s[12:13]
	s_lshl_b64 s[12:13], s[28:29], 14
	s_or_b32 s28, s48, 6
	global_load_dword v51, v[12:13], off
	v_lshl_add_u64 v[12:13], v[26:27], 0, s[12:13]
	s_lshl_b64 s[12:13], s[28:29], 16
	global_load_dword v52, v[12:13], off
	v_lshl_add_u64 v[12:13], v[24:25], 0, s[12:13]
	s_lshl_b64 s[12:13], s[28:29], 14
	s_or_b32 s28, s48, 7
	global_load_dword v53, v[12:13], off
	v_lshl_add_u64 v[12:13], v[26:27], 0, s[12:13]
	s_lshl_b64 s[12:13], s[28:29], 16
	global_load_dword v54, v[12:13], off
	v_lshl_add_u64 v[12:13], v[24:25], 0, s[12:13]
	s_lshl_b64 s[12:13], s[28:29], 14
	s_or_b32 s28, s48, 8
	global_load_dword v55, v[12:13], off
	v_lshl_add_u64 v[12:13], v[26:27], 0, s[12:13]
	s_lshl_b64 s[12:13], s[28:29], 16
	global_load_dword v56, v[12:13], off
	v_lshl_add_u64 v[12:13], v[24:25], 0, s[12:13]
	s_lshl_b64 s[12:13], s[28:29], 14
	s_or_b32 s28, s48, 9
	global_load_dword v57, v[12:13], off
	v_lshl_add_u64 v[12:13], v[26:27], 0, s[12:13]
	s_lshl_b64 s[12:13], s[28:29], 16
	global_load_dword v58, v[12:13], off
	v_lshl_add_u64 v[12:13], v[24:25], 0, s[12:13]
	s_lshl_b64 s[12:13], s[28:29], 14
	s_or_b32 s28, s48, 10
	global_load_dword v59, v[12:13], off
	v_lshl_add_u64 v[12:13], v[26:27], 0, s[12:13]
	s_lshl_b64 s[12:13], s[28:29], 16
	global_load_dword v60, v[12:13], off
	v_lshl_add_u64 v[12:13], v[24:25], 0, s[12:13]
	s_lshl_b64 s[12:13], s[28:29], 14
	s_or_b32 s28, s48, 11
	global_load_dword v61, v[12:13], off
	v_lshl_add_u64 v[12:13], v[26:27], 0, s[12:13]
	s_lshl_b64 s[12:13], s[28:29], 16
	global_load_dword v62, v[12:13], off
	v_lshl_add_u64 v[12:13], v[24:25], 0, s[12:13]
	s_lshl_b64 s[12:13], s[28:29], 14
	s_or_b32 s28, s48, 12
	global_load_dword v63, v[12:13], off
	v_lshl_add_u64 v[12:13], v[26:27], 0, s[12:13]
	s_lshl_b64 s[12:13], s[28:29], 16
	global_load_dword v64, v[12:13], off
	v_lshl_add_u64 v[12:13], v[24:25], 0, s[12:13]
	s_lshl_b64 s[12:13], s[28:29], 14
	s_or_b32 s28, s48, 13
	v_lshl_add_u64 v[14:15], v[26:27], 0, s[12:13]
	s_lshl_b64 s[12:13], s[28:29], 16
	v_lshl_add_u64 v[16:17], v[24:25], 0, s[12:13]
	s_lshl_b64 s[12:13], s[28:29], 14
	s_or_b32 s28, s48, 14
	global_load_dword v12, v[12:13], off
	s_nop 0
	global_load_dword v14, v[14:15], off
	s_nop 0
	global_load_dword v13, v[16:17], off
	v_lshl_add_u64 v[16:17], v[26:27], 0, s[12:13]
	s_lshl_b64 s[12:13], s[28:29], 16
	global_load_dword v15, v[16:17], off
	v_lshl_add_u64 v[16:17], v[24:25], 0, s[12:13]
	s_lshl_b64 s[12:13], s[28:29], 14
	s_or_b32 s28, s48, 15
	v_lshl_add_u64 v[18:19], v[26:27], 0, s[12:13]
	s_lshl_b64 s[12:13], s[28:29], 16
	v_lshl_add_u64 v[22:23], v[24:25], 0, s[12:13]
	s_lshl_b64 s[12:13], s[28:29], 14
	global_load_dword v16, v[16:17], off
	s_nop 0
	global_load_dword v18, v[18:19], off
	s_nop 0
	global_load_dword v17, v[22:23], off
	v_lshl_add_u64 v[22:23], v[26:27], 0, s[12:13]
	global_load_dword v19, v[22:23], off
	s_branch .LBB0_155

.LBB0_155:
	v_lshl_add_u64 v[22:23], v[0:1], 0, s[10:11]
	v_cvt_pk_bf16_f32 v28, v10, v11
	global_store_dword v[22:23], v28, off
	v_lshl_add_u64 v[22:23], v[2:3], 0, s[8:9]
	s_lshl_b32 s8, s48, 2
	v_cvt_pk_bf16_f32 v28, v21, v20
	s_add_i32 s10, s8, 16
	global_store_dword v[22:23], v28, off
	v_mov_b32_e32 v28, s10
	ds_read2_b32 v[22:23], v28 offset1:32
	ds_read_b32 v29, v28 offset:256
	s_and_saveexec_b64 s[8:9], s[42:43]
	s_cbranch_execz .LBB0_157
	v_lshl_or_b32 v30, s48, 7, v65
	v_ashrrev_i32_e32 v31, 31, v30
	v_lshlrev_b64 v[30:31], 2, v[30:31]
	v_lshl_add_u64 v[32:33], v[4:5], 0, v[30:31]
	v_mov_b32_e32 v30, v80
	v_mov_b32_e32 v31, v81
	s_nop 0
	global_store_dwordx2 v[32:33], v[8:9], off
	s_waitcnt lgkmcnt(1)
	v_mul_f32_e32 v8, v8, v22
	v_mul_f32_e32 v32, v23, v30
	v_mov_b32_e32 v30, v9
	v_pk_mul_f32 v[30:31], v[30:31], v[22:23]
	s_nop 0
	v_mov_b32_e32 v9, v30
	v_mov_b32_e32 v33, v31
	v_pk_add_f32 v[8:9], v[8:9], v[32:33]
.LBB0_157:
	s_or_b64 exec, exec, s[8:9]
	s_waitcnt vmcnt(33)
	v_lshlrev_b32_e32 v28, 16, v41
	s_waitcnt lgkmcnt(1)
	v_mul_f32_e32 v28, v23, v28
	v_fmac_f32_e32 v28, v10, v22
	v_and_b32_e32 v10, 0xffff0000, v41
	v_mul_f32_e32 v23, v23, v10
	v_fmac_f32_e32 v23, v11, v22
	s_waitcnt vmcnt(32)
	v_lshlrev_b32_e32 v22, 16, v42
	s_or_b32 s28, s48, 1
	s_waitcnt lgkmcnt(0)
	v_fmac_f32_e32 v22, v21, v29
	v_and_b32_e32 v21, 0xffff0000, v42
	s_lshl_b64 s[8:9], s[28:29], 16
	v_fmac_f32_e32 v21, v20, v29
	v_cvt_pk_bf16_f32 v20, v28, v23
	v_lshl_add_u64 v[10:11], v[0:1], 0, s[8:9]
	s_lshl_b64 s[8:9], s[28:29], 14
	global_store_dword v[10:11], v20, off
	v_cvt_pk_bf16_f32 v20, v22, v21
	v_lshl_add_u64 v[10:11], v[2:3], 0, s[8:9]
	global_store_dword v[10:11], v20, off
	v_mov_b32_e32 v20, s10
	ds_read2_b32 v[10:11], v20 offset0:1 offset1:33
	ds_read_b32 v29, v20 offset:260
	s_and_saveexec_b64 s[8:9], s[42:43]
	s_cbranch_execz .LBB0_159
	v_lshl_or_b32 v30, s28, 7, v65
	v_ashrrev_i32_e32 v31, 31, v30
	v_lshlrev_b64 v[30:31], 2, v[30:31]
	v_lshl_add_u64 v[32:33], v[4:5], 0, v[30:31]
	v_mov_b32_e32 v30, v82
	v_mov_b32_e32 v31, v83
	s_waitcnt lgkmcnt(1)
	v_mov_b32_e32 v20, v11
	global_store_dwordx2 v[32:33], v[8:9], off
	v_pk_mul_f32 v[30:31], v[20:21], v[30:31] op_sel_hi:[0,1]
	v_pk_fma_f32 v[8:9], v[8:9], v[10:11], v[30:31] op_sel_hi:[1,0,1]
.LBB0_159:
	s_or_b64 exec, exec, s[8:9]
	s_waitcnt vmcnt(33)
	v_lshlrev_b32_e32 v20, 16, v43
	s_waitcnt lgkmcnt(1)
	v_mul_f32_e32 v20, v11, v20
	v_fmac_f32_e32 v20, v28, v10
	v_and_b32_e32 v28, 0xffff0000, v43
	v_mul_f32_e32 v28, v11, v28
	v_fmac_f32_e32 v28, v23, v10
	s_waitcnt vmcnt(32)
	v_lshlrev_b32_e32 v23, 16, v44
	s_or_b32 s28, s48, 2
	s_waitcnt lgkmcnt(0)
	v_fmac_f32_e32 v23, v22, v29
	v_and_b32_e32 v22, 0xffff0000, v44
	s_lshl_b64 s[8:9], s[28:29], 16
	v_fmac_f32_e32 v22, v21, v29
	v_cvt_pk_bf16_f32 v21, v20, v28
	v_lshl_add_u64 v[10:11], v[0:1], 0, s[8:9]
	s_lshl_b64 s[8:9], s[28:29], 14
	global_store_dword v[10:11], v21, off
	v_cvt_pk_bf16_f32 v21, v23, v22
	v_lshl_add_u64 v[10:11], v[2:3], 0, s[8:9]
	global_store_dword v[10:11], v21, off
	v_mov_b32_e32 v21, s10
	ds_read2_b32 v[10:11], v21 offset0:2 offset1:34
	ds_read_b32 v29, v21 offset:264
	s_and_saveexec_b64 s[8:9], s[42:43]
	s_cbranch_execz .LBB0_161
	v_lshl_or_b32 v30, s28, 7, v65
	v_ashrrev_i32_e32 v31, 31, v30
	v_lshlrev_b64 v[30:31], 2, v[30:31]
	v_lshl_add_u64 v[32:33], v[4:5], 0, v[30:31]
	v_mov_b32_e32 v30, v84
	v_mov_b32_e32 v31, v85
	s_nop 0
	global_store_dwordx2 v[32:33], v[8:9], off
	s_waitcnt lgkmcnt(1)
	v_mov_b32_e32 v32, v11
	v_pk_mul_f32 v[30:31], v[32:33], v[30:31] op_sel_hi:[0,1]
	v_pk_fma_f32 v[8:9], v[8:9], v[10:11], v[30:31] op_sel_hi:[1,0,1]
.LBB0_161:
	s_or_b64 exec, exec, s[8:9]
	s_waitcnt vmcnt(33)
	v_lshlrev_b32_e32 v21, 16, v45
	s_waitcnt lgkmcnt(1)
	v_mul_f32_e32 v21, v11, v21
	v_fmac_f32_e32 v21, v20, v10
	v_and_b32_e32 v20, 0xffff0000, v45
	v_mul_f32_e32 v20, v11, v20
	v_fmac_f32_e32 v20, v28, v10
	s_waitcnt vmcnt(32)
	v_lshlrev_b32_e32 v28, 16, v46
	s_or_b32 s28, s48, 3
	s_waitcnt lgkmcnt(0)
	v_fmac_f32_e32 v28, v23, v29
	v_and_b32_e32 v23, 0xffff0000, v46
	s_lshl_b64 s[8:9], s[28:29], 16
	v_fmac_f32_e32 v23, v22, v29
	v_cvt_pk_bf16_f32 v22, v21, v20
	v_lshl_add_u64 v[10:11], v[0:1], 0, s[8:9]
	s_lshl_b64 s[8:9], s[28:29], 14
	global_store_dword v[10:11], v22, off
	v_cvt_pk_bf16_f32 v22, v28, v23
	v_lshl_add_u64 v[10:11], v[2:3], 0, s[8:9]
	global_store_dword v[10:11], v22, off
	v_mov_b32_e32 v22, s10
	ds_read2_b32 v[10:11], v22 offset0:3 offset1:35
	ds_read_b32 v31, v22 offset:268
	s_and_saveexec_b64 s[8:9], s[42:43]
	s_cbranch_execz .LBB0_163
	v_lshl_or_b32 v32, s28, 7, v65
	v_ashrrev_i32_e32 v33, 31, v32
	v_lshlrev_b64 v[32:33], 2, v[32:33]
	v_lshl_add_u64 v[66:67], v[4:5], 0, v[32:33]
	v_mov_b32_e32 v32, v86
	v_mov_b32_e32 v33, v87
	s_waitcnt lgkmcnt(1)
	v_mov_b32_e32 v22, v11
	global_store_dwordx2 v[66:67], v[8:9], off
	v_pk_mul_f32 v[32:33], v[22:23], v[32:33] op_sel_hi:[0,1]
	v_pk_fma_f32 v[8:9], v[8:9], v[10:11], v[32:33] op_sel_hi:[1,0,1]
.LBB0_163:
	s_or_b64 exec, exec, s[8:9]
	s_waitcnt vmcnt(33)
	v_lshlrev_b32_e32 v22, 16, v47
	s_waitcnt lgkmcnt(1)
	v_mul_f32_e32 v22, v11, v22
	v_fmac_f32_e32 v22, v21, v10
	v_and_b32_e32 v21, 0xffff0000, v47
	s_or_b32 s28, s48, 4
	v_mul_f32_e32 v29, v11, v21
	s_waitcnt vmcnt(32)
	v_lshlrev_b32_e32 v30, 16, v48
	s_lshl_b64 s[8:9], s[28:29], 16
	v_fmac_f32_e32 v29, v20, v10
	s_waitcnt lgkmcnt(0)
	v_fmac_f32_e32 v30, v28, v31
	v_and_b32_e32 v28, 0xffff0000, v48
	v_cvt_pk_bf16_f32 v20, v22, v29
	v_lshl_add_u64 v[10:11], v[0:1], 0, s[8:9]
	s_lshl_b64 s[8:9], s[28:29], 14
	v_fmac_f32_e32 v28, v23, v31
	global_store_dword v[10:11], v20, off
	v_cvt_pk_bf16_f32 v20, v30, v28
	v_lshl_add_u64 v[10:11], v[2:3], 0, s[8:9]
	global_store_dword v[10:11], v20, off
	v_mov_b32_e32 v20, s10
	ds_read2_b32 v[10:11], v20 offset0:4 offset1:36
	ds_read_b32 v31, v20 offset:272
	s_and_saveexec_b64 s[8:9], s[42:43]
	s_cbranch_execz .LBB0_165
	v_lshl_or_b32 v20, s28, 7, v65
	v_ashrrev_i32_e32 v21, 31, v20
	v_lshlrev_b64 v[20:21], 2, v[20:21]
	v_lshl_add_u64 v[32:33], v[4:5], 0, v[20:21]
	v_mov_b32_e32 v20, v88
	v_mov_b32_e32 v21, v89
	s_nop 0
	global_store_dwordx2 v[32:33], v[8:9], off
	s_waitcnt lgkmcnt(1)
	v_mov_b32_e32 v32, v11
	v_pk_mul_f32 v[20:21], v[32:33], v[20:21] op_sel_hi:[0,1]
	v_pk_fma_f32 v[8:9], v[8:9], v[10:11], v[20:21] op_sel_hi:[1,0,1]
.LBB0_165:
	s_or_b64 exec, exec, s[8:9]
	s_waitcnt vmcnt(33)
	v_lshlrev_b32_e32 v20, 16, v49
	v_and_b32_e32 v21, 0xffff0000, v49
	s_or_b32 s28, s48, 5
	s_waitcnt lgkmcnt(1)
	v_mul_f32_e32 v20, v11, v20
	v_mul_f32_e32 v21, v11, v21
	s_waitcnt vmcnt(32)
	v_and_b32_e32 v23, 0xffff0000, v50
	s_lshl_b64 s[8:9], s[28:29], 16
	v_fmac_f32_e32 v20, v22, v10
	v_fmac_f32_e32 v21, v29, v10
	v_lshlrev_b32_e32 v22, 16, v50
	s_waitcnt lgkmcnt(0)
	v_fmac_f32_e32 v23, v28, v31
	v_cvt_pk_bf16_f32 v28, v20, v21
	v_lshl_add_u64 v[10:11], v[0:1], 0, s[8:9]
	s_lshl_b64 s[8:9], s[28:29], 14
	v_fmac_f32_e32 v22, v30, v31
	global_store_dword v[10:11], v28, off
	v_cvt_pk_bf16_f32 v28, v22, v23
	v_lshl_add_u64 v[10:11], v[2:3], 0, s[8:9]
	global_store_dword v[10:11], v28, off
	v_mov_b32_e32 v28, s10
	ds_read2_b32 v[10:11], v28 offset0:5 offset1:37
	ds_read_b32 v29, v28 offset:276
	s_and_saveexec_b64 s[8:9], s[42:43]
	s_cbranch_execz .LBB0_167
	v_lshl_or_b32 v30, s28, 7, v65
	v_ashrrev_i32_e32 v31, 31, v30
	v_lshlrev_b64 v[30:31], 2, v[30:31]
	v_lshl_add_u64 v[32:33], v[4:5], 0, v[30:31]
	v_mov_b32_e32 v30, v90
	v_mov_b32_e32 v31, v91
	s_nop 0
	global_store_dwordx2 v[32:33], v[8:9], off
	s_waitcnt lgkmcnt(1)
	v_mul_f32_e32 v8, v8, v10
	v_mul_f32_e32 v32, v11, v30
	v_mov_b32_e32 v30, v9
	v_pk_mul_f32 v[30:31], v[30:31], v[10:11]
	s_nop 0
	v_mov_b32_e32 v9, v30
	v_mov_b32_e32 v33, v31
	v_pk_add_f32 v[8:9], v[8:9], v[32:33]
.LBB0_167:
	s_or_b64 exec, exec, s[8:9]
	s_waitcnt vmcnt(33)
	v_lshlrev_b32_e32 v28, 16, v51
	s_waitcnt lgkmcnt(1)
	v_mul_f32_e32 v28, v11, v28
	v_fmac_f32_e32 v28, v20, v10
	v_and_b32_e32 v20, 0xffff0000, v51
	v_mul_f32_e32 v20, v11, v20
	v_fmac_f32_e32 v20, v21, v10
	s_waitcnt vmcnt(32)
	v_lshlrev_b32_e32 v21, 16, v52
	s_or_b32 s28, s48, 6
	s_waitcnt lgkmcnt(0)
	v_fmac_f32_e32 v21, v22, v29
	v_and_b32_e32 v22, 0xffff0000, v52
	s_lshl_b64 s[8:9], s[28:29], 16
	v_fmac_f32_e32 v22, v23, v29
	v_cvt_pk_bf16_f32 v23, v28, v20
	v_lshl_add_u64 v[10:11], v[0:1], 0, s[8:9]
	s_lshl_b64 s[8:9], s[28:29], 14
	global_store_dword v[10:11], v23, off
	v_cvt_pk_bf16_f32 v23, v21, v22
	v_lshl_add_u64 v[10:11], v[2:3], 0, s[8:9]
	global_store_dword v[10:11], v23, off
	v_mov_b32_e32 v23, s10
	ds_read2_b32 v[10:11], v23 offset0:6 offset1:38
	ds_read_b32 v29, v23 offset:280
	s_and_saveexec_b64 s[8:9], s[42:43]
	s_cbranch_execz .LBB0_169
	v_lshl_or_b32 v30, s28, 7, v65
	v_ashrrev_i32_e32 v31, 31, v30
	v_lshlrev_b64 v[30:31], 2, v[30:31]
	v_lshl_add_u64 v[32:33], v[4:5], 0, v[30:31]
	v_mov_b32_e32 v30, v92
	v_mov_b32_e32 v31, v93
	s_nop 0
	global_store_dwordx2 v[32:33], v[8:9], off
	s_waitcnt lgkmcnt(1)
	v_mov_b32_e32 v32, v11
	v_pk_mul_f32 v[30:31], v[32:33], v[30:31] op_sel_hi:[0,1]
	v_pk_fma_f32 v[8:9], v[8:9], v[10:11], v[30:31] op_sel_hi:[1,0,1]
.LBB0_169:
	s_or_b64 exec, exec, s[8:9]
	s_waitcnt vmcnt(33)
	v_lshlrev_b32_e32 v23, 16, v53
	s_waitcnt lgkmcnt(1)
	v_mul_f32_e32 v23, v11, v23
	v_fmac_f32_e32 v23, v28, v10
	v_and_b32_e32 v28, 0xffff0000, v53
	v_mul_f32_e32 v28, v11, v28
	v_fmac_f32_e32 v28, v20, v10
	s_waitcnt vmcnt(32)
	v_lshlrev_b32_e32 v20, 16, v54
	s_or_b32 s28, s48, 7
	s_waitcnt lgkmcnt(0)
	v_fmac_f32_e32 v20, v21, v29
	v_and_b32_e32 v21, 0xffff0000, v54
	s_lshl_b64 s[8:9], s[28:29], 16
	v_fmac_f32_e32 v21, v22, v29
	v_cvt_pk_bf16_f32 v22, v23, v28
	v_lshl_add_u64 v[10:11], v[0:1], 0, s[8:9]
	s_lshl_b64 s[8:9], s[28:29], 14
	global_store_dword v[10:11], v22, off
	v_cvt_pk_bf16_f32 v22, v20, v21
	v_lshl_add_u64 v[10:11], v[2:3], 0, s[8:9]
	global_store_dword v[10:11], v22, off
	v_mov_b32_e32 v22, s10
	ds_read2_b32 v[10:11], v22 offset0:7 offset1:39
	ds_read_b32 v29, v22 offset:284
	s_and_saveexec_b64 s[8:9], s[42:43]
	s_cbranch_execz .LBB0_171
	v_lshl_or_b32 v30, s28, 7, v65
	v_ashrrev_i32_e32 v31, 31, v30
	v_lshlrev_b64 v[30:31], 2, v[30:31]
	v_lshl_add_u64 v[32:33], v[4:5], 0, v[30:31]
	v_mov_b32_e32 v30, v94
	v_mov_b32_e32 v31, v95
	s_waitcnt lgkmcnt(1)
	v_mov_b32_e32 v22, v11
	global_store_dwordx2 v[32:33], v[8:9], off
	v_pk_mul_f32 v[30:31], v[22:23], v[30:31] op_sel_hi:[0,1]
	v_pk_fma_f32 v[8:9], v[8:9], v[10:11], v[30:31] op_sel_hi:[1,0,1]
.LBB0_171:
	s_or_b64 exec, exec, s[8:9]
	s_waitcnt vmcnt(33)
	v_lshlrev_b32_e32 v22, 16, v55
	s_waitcnt lgkmcnt(1)
	v_mul_f32_e32 v22, v11, v22
	v_fmac_f32_e32 v22, v23, v10
	v_and_b32_e32 v23, 0xffff0000, v55
	v_mul_f32_e32 v23, v11, v23
	v_fmac_f32_e32 v23, v28, v10
	s_waitcnt vmcnt(32)
	v_lshlrev_b32_e32 v28, 16, v56
	s_or_b32 s28, s48, 8
	s_waitcnt lgkmcnt(0)
	v_fmac_f32_e32 v28, v20, v29
	v_and_b32_e32 v20, 0xffff0000, v56
	s_lshl_b64 s[8:9], s[28:29], 16
	v_fmac_f32_e32 v20, v21, v29
	v_cvt_pk_bf16_f32 v21, v22, v23
	v_lshl_add_u64 v[10:11], v[0:1], 0, s[8:9]
	s_lshl_b64 s[8:9], s[28:29], 14
	global_store_dword v[10:11], v21, off
	v_cvt_pk_bf16_f32 v21, v28, v20
	v_lshl_add_u64 v[10:11], v[2:3], 0, s[8:9]
	global_store_dword v[10:11], v21, off
	v_mov_b32_e32 v21, s10
	ds_read2_b32 v[10:11], v21 offset0:8 offset1:40
	ds_read_b32 v31, v21 offset:288
	s_and_saveexec_b64 s[8:9], s[42:43]
	s_cbranch_execz .LBB0_173
	v_lshl_or_b32 v32, s28, 7, v65
	v_ashrrev_i32_e32 v33, 31, v32
	v_lshlrev_b64 v[32:33], 2, v[32:33]
	v_lshl_add_u64 v[66:67], v[4:5], 0, v[32:33]
	v_mov_b32_e32 v32, v96
	v_mov_b32_e32 v33, v97
	s_waitcnt lgkmcnt(1)
	v_mov_b32_e32 v30, v11
	global_store_dwordx2 v[66:67], v[8:9], off
	s_waitcnt lgkmcnt(0)
	v_pk_mul_f32 v[32:33], v[30:31], v[32:33] op_sel_hi:[0,1]
	v_pk_fma_f32 v[8:9], v[8:9], v[10:11], v[32:33] op_sel_hi:[1,0,1]
.LBB0_173:
	s_or_b64 exec, exec, s[8:9]
	s_waitcnt vmcnt(33)
	v_lshlrev_b32_e32 v21, 16, v57
	s_waitcnt lgkmcnt(1)
	v_mul_f32_e32 v21, v11, v21
	v_fmac_f32_e32 v21, v22, v10
	v_and_b32_e32 v22, 0xffff0000, v57
	s_waitcnt vmcnt(32)
	v_lshlrev_b32_e32 v30, 16, v58
	s_or_b32 s28, s48, 9
	v_mul_f32_e32 v29, v11, v22
	s_waitcnt lgkmcnt(0)
	v_fmac_f32_e32 v30, v28, v31
	v_and_b32_e32 v28, 0xffff0000, v58
	s_lshl_b64 s[8:9], s[28:29], 16
	v_fmac_f32_e32 v29, v23, v10
	v_fmac_f32_e32 v28, v20, v31
	v_cvt_pk_bf16_f32 v20, v21, v29
	v_lshl_add_u64 v[10:11], v[0:1], 0, s[8:9]
	s_lshl_b64 s[8:9], s[28:29], 14
	global_store_dword v[10:11], v20, off
	v_cvt_pk_bf16_f32 v20, v30, v28
	v_lshl_add_u64 v[10:11], v[2:3], 0, s[8:9]
	global_store_dword v[10:11], v20, off
	v_mov_b32_e32 v20, s10
	ds_read2_b32 v[10:11], v20 offset0:9 offset1:41
	ds_read_b32 v31, v20 offset:292
	s_and_saveexec_b64 s[8:9], s[42:43]
	s_cbranch_execz .LBB0_175
	v_lshl_or_b32 v22, s28, 7, v65
	v_ashrrev_i32_e32 v23, 31, v22
	v_lshlrev_b64 v[22:23], 2, v[22:23]
	v_lshl_add_u64 v[32:33], v[4:5], 0, v[22:23]
	v_mov_b32_e32 v22, v98
	v_mov_b32_e32 v23, v99
	s_waitcnt lgkmcnt(1)
	v_mov_b32_e32 v20, v11
	global_store_dwordx2 v[32:33], v[8:9], off
	v_pk_mul_f32 v[22:23], v[20:21], v[22:23] op_sel_hi:[0,1]
	v_pk_fma_f32 v[8:9], v[8:9], v[10:11], v[22:23] op_sel_hi:[1,0,1]
.LBB0_175:
	s_or_b64 exec, exec, s[8:9]
	s_waitcnt vmcnt(33)
	v_lshlrev_b32_e32 v20, 16, v59
	s_waitcnt lgkmcnt(1)
	v_mul_f32_e32 v22, v11, v20
	v_and_b32_e32 v20, 0xffff0000, v59
	s_or_b32 s28, s48, 10
	v_fmac_f32_e32 v22, v21, v10
	v_mul_f32_e32 v23, v11, v20
	s_waitcnt vmcnt(32)
	v_and_b32_e32 v21, 0xffff0000, v60
	s_lshl_b64 s[8:9], s[28:29], 16
	v_fmac_f32_e32 v23, v29, v10
	v_lshlrev_b32_e32 v20, 16, v60
	s_waitcnt lgkmcnt(0)
	v_fmac_f32_e32 v21, v28, v31
	v_cvt_pk_bf16_f32 v28, v22, v23
	v_lshl_add_u64 v[10:11], v[0:1], 0, s[8:9]
	s_lshl_b64 s[8:9], s[28:29], 14
	v_fmac_f32_e32 v20, v30, v31
	global_store_dword v[10:11], v28, off
	v_cvt_pk_bf16_f32 v28, v20, v21
	v_lshl_add_u64 v[10:11], v[2:3], 0, s[8:9]
	global_store_dword v[10:11], v28, off
	v_mov_b32_e32 v28, s10
	ds_read2_b32 v[10:11], v28 offset0:10 offset1:42
	ds_read_b32 v28, v28 offset:296
	s_and_saveexec_b64 s[8:9], s[42:43]
	s_cbranch_execz .LBB0_177
	v_lshl_or_b32 v30, s28, 7, v65
	v_ashrrev_i32_e32 v31, 31, v30
	v_lshlrev_b64 v[30:31], 2, v[30:31]
	v_lshl_add_u64 v[32:33], v[4:5], 0, v[30:31]
	v_mov_b32_e32 v30, v100
	v_mov_b32_e32 v31, v101
	s_nop 0
	global_store_dwordx2 v[32:33], v[8:9], off
	s_waitcnt lgkmcnt(1)
	v_mul_f32_e32 v8, v8, v10
	v_mul_f32_e32 v32, v11, v30
	v_mov_b32_e32 v30, v9
	v_pk_mul_f32 v[30:31], v[30:31], v[10:11]
	s_nop 0
	v_mov_b32_e32 v9, v30
	v_mov_b32_e32 v33, v31
	v_pk_add_f32 v[8:9], v[8:9], v[32:33]
.LBB0_177:
	s_or_b64 exec, exec, s[8:9]
	s_waitcnt lgkmcnt(1)
	v_mul_f32_e32 v22, v22, v10
	s_waitcnt vmcnt(33)
	v_lshlrev_b32_e32 v29, 16, v61
	v_mul_f32_e32 v23, v23, v10
	v_and_b32_e32 v10, 0xffff0000, v61
	v_mul_f32_e32 v30, v11, v29
	v_mul_f32_e32 v31, v11, v10
	s_or_b32 s28, s48, 11
	v_pk_add_f32 v[10:11], v[22:23], v[30:31]
	s_waitcnt lgkmcnt(0)
	v_mul_f32_e32 v23, v20, v28
	s_waitcnt vmcnt(32)
	v_lshlrev_b32_e32 v29, 16, v62
	v_mul_f32_e32 v22, v21, v28
	v_and_b32_e32 v28, 0xffff0000, v62
	s_lshl_b64 s[8:9], s[28:29], 16
	v_pk_add_f32 v[20:21], v[22:23], v[28:29]
	v_lshl_add_u64 v[22:23], v[0:1], 0, s[8:9]
	v_cvt_pk_bf16_f32 v28, v10, v11
	global_store_dword v[22:23], v28, off
	v_mov_b32_e32 v22, s10
	ds_read2_b32 v[28:29], v22 offset0:11 offset1:43
	ds_read_b32 v22, v22 offset:300
	s_lshl_b64 s[8:9], s[28:29], 14
	v_lshl_add_u64 v[30:31], v[2:3], 0, s[8:9]
	v_cvt_pk_bf16_f32 v23, v21, v20
	global_store_dword v[30:31], v23, off
	s_waitcnt lgkmcnt(1)
	v_mov_b32_e32 v30, v29
	v_mov_b64_e32 v[32:33], v[28:29]
	s_and_saveexec_b64 s[8:9], s[44:45]
	s_xor_b64 s[8:9], exec, s[8:9]
	v_mov_b32_e32 v30, v29
	v_mov_b64_e32 v[32:33], v[28:29]
	s_andn2_saveexec_b64 s[8:9], s[8:9]
	s_cbranch_execz .LBB0_181
	v_lshl_or_b32 v66, s28, 7, v65
	v_ashrrev_i32_e32 v67, 31, v66
	v_lshlrev_b64 v[66:67], 2, v[66:67]
	v_lshl_add_u64 v[68:69], v[4:5], 0, v[66:67]
	v_mov_b32_e32 v66, v102
	v_mov_b32_e32 v67, v103
	v_pk_mul_f32 v[66:67], v[30:31], v[66:67] op_sel_hi:[0,1]
	global_store_dwordx2 v[68:69], v[8:9], off
	v_pk_fma_f32 v[8:9], v[8:9], v[28:29], v[66:67] op_sel_hi:[1,0,1]
.LBB0_181:
	s_or_b64 exec, exec, s[8:9]
	v_mov_b32_e32 v33, v28
	v_mov_b32_e32 v31, v29
	s_waitcnt vmcnt(33)
	v_lshlrev_b32_e32 v28, 16, v63
	v_and_b32_e32 v29, 0xffff0000, v63
	v_pk_mul_f32 v[28:29], v[30:31], v[28:29]
	s_or_b32 s28, s48, 12
	v_pk_fma_f32 v[10:11], v[10:11], v[32:33], v[28:29]
	s_waitcnt vmcnt(32)
	v_lshlrev_b32_e32 v29, 16, v64
	v_and_b32_e32 v28, 0xffff0000, v64
	s_lshl_b64 s[8:9], s[28:29], 16
	s_waitcnt lgkmcnt(0)
	v_pk_fma_f32 v[20:21], v[20:21], v[22:23], v[28:29] op_sel_hi:[1,0,1]
	v_lshl_add_u64 v[22:23], v[0:1], 0, s[8:9]
	v_cvt_pk_bf16_f32 v28, v10, v11
	global_store_dword v[22:23], v28, off
	v_mov_b32_e32 v22, s10
	ds_read2_b32 v[28:29], v22 offset0:12 offset1:44
	ds_read_b32 v22, v22 offset:304
	s_lshl_b64 s[8:9], s[28:29], 14
	v_lshl_add_u64 v[30:31], v[2:3], 0, s[8:9]
	v_cvt_pk_bf16_f32 v23, v21, v20
	global_store_dword v[30:31], v23, off
	s_waitcnt lgkmcnt(1)
	v_mov_b32_e32 v30, v29
	v_mov_b64_e32 v[32:33], v[28:29]
	s_and_saveexec_b64 s[8:9], s[44:45]
	s_xor_b64 s[8:9], exec, s[8:9]
	v_mov_b32_e32 v30, v29
	v_mov_b64_e32 v[32:33], v[28:29]
	s_andn2_saveexec_b64 s[8:9], s[8:9]
	s_cbranch_execz .LBB0_185
	v_lshl_or_b32 v66, s28, 7, v65
	v_ashrrev_i32_e32 v67, 31, v66
	v_lshlrev_b64 v[66:67], 2, v[66:67]
	v_lshl_add_u64 v[68:69], v[4:5], 0, v[66:67]
	v_mov_b32_e32 v66, v104
	v_mov_b32_e32 v67, v105
	v_pk_mul_f32 v[66:67], v[30:31], v[66:67] op_sel_hi:[0,1]
	global_store_dwordx2 v[68:69], v[8:9], off
	v_pk_fma_f32 v[8:9], v[8:9], v[28:29], v[66:67] op_sel_hi:[1,0,1]
.LBB0_185:
	s_or_b64 exec, exec, s[8:9]
	v_mov_b32_e32 v33, v28
	v_mov_b32_e32 v31, v29
	s_waitcnt vmcnt(33)
	v_lshlrev_b32_e32 v28, 16, v12
	v_and_b32_e32 v29, 0xffff0000, v12
	v_pk_mul_f32 v[28:29], v[30:31], v[28:29]
	s_or_b32 s28, s48, 13
	v_pk_fma_f32 v[10:11], v[10:11], v[32:33], v[28:29]
	s_waitcnt vmcnt(32)
	v_and_b32_e32 v28, 0xffff0000, v14
	v_lshlrev_b32_e32 v29, 16, v14
	s_lshl_b64 s[8:9], s[28:29], 16
	s_waitcnt lgkmcnt(0)
	v_pk_fma_f32 v[20:21], v[20:21], v[22:23], v[28:29] op_sel_hi:[1,0,1]
	v_lshl_add_u64 v[22:23], v[0:1], 0, s[8:9]
	v_cvt_pk_bf16_f32 v28, v10, v11
	global_store_dword v[22:23], v28, off
	v_mov_b32_e32 v22, s10
	ds_read2_b32 v[28:29], v22 offset0:13 offset1:45
	ds_read_b32 v22, v22 offset:308
	s_lshl_b64 s[8:9], s[28:29], 14
	v_lshl_add_u64 v[30:31], v[2:3], 0, s[8:9]
	v_cvt_pk_bf16_f32 v23, v21, v20
	global_store_dword v[30:31], v23, off
	s_waitcnt lgkmcnt(1)
	v_mov_b32_e32 v30, v29
	v_mov_b64_e32 v[32:33], v[28:29]
	s_and_saveexec_b64 s[8:9], s[44:45]
	s_xor_b64 s[8:9], exec, s[8:9]
	v_mov_b32_e32 v30, v29
	v_mov_b64_e32 v[32:33], v[28:29]
	s_andn2_saveexec_b64 s[8:9], s[8:9]
	s_cbranch_execz .LBB0_189
	v_lshl_or_b32 v66, s28, 7, v65
	v_ashrrev_i32_e32 v67, 31, v66
	v_lshlrev_b64 v[66:67], 2, v[66:67]
	v_lshl_add_u64 v[68:69], v[4:5], 0, v[66:67]
	v_mov_b32_e32 v66, v106
	v_mov_b32_e32 v67, v107
	v_pk_mul_f32 v[66:67], v[30:31], v[66:67] op_sel_hi:[0,1]
	global_store_dwordx2 v[68:69], v[8:9], off
	v_pk_fma_f32 v[8:9], v[8:9], v[28:29], v[66:67] op_sel_hi:[1,0,1]
.LBB0_189:
	s_or_b64 exec, exec, s[8:9]
	v_mov_b32_e32 v33, v28
	v_mov_b32_e32 v31, v29
	s_waitcnt vmcnt(33)
	v_lshlrev_b32_e32 v28, 16, v13
	v_and_b32_e32 v29, 0xffff0000, v13
	v_pk_mul_f32 v[28:29], v[30:31], v[28:29]
	s_or_b32 s28, s48, 14
	v_pk_fma_f32 v[10:11], v[10:11], v[32:33], v[28:29]
	s_waitcnt vmcnt(32)
	v_and_b32_e32 v28, 0xffff0000, v15
	v_lshlrev_b32_e32 v29, 16, v15
	s_lshl_b64 s[8:9], s[28:29], 16
	s_waitcnt lgkmcnt(0)
	v_pk_fma_f32 v[20:21], v[20:21], v[22:23], v[28:29] op_sel_hi:[1,0,1]
	v_lshl_add_u64 v[22:23], v[0:1], 0, s[8:9]
	v_cvt_pk_bf16_f32 v28, v10, v11
	global_store_dword v[22:23], v28, off
	v_mov_b32_e32 v22, s10
	ds_read2_b32 v[28:29], v22 offset0:14 offset1:46
	ds_read_b32 v22, v22 offset:312
	s_lshl_b64 s[8:9], s[28:29], 14
	v_lshl_add_u64 v[30:31], v[2:3], 0, s[8:9]
	v_cvt_pk_bf16_f32 v23, v21, v20
	global_store_dword v[30:31], v23, off
	s_waitcnt lgkmcnt(1)
	v_mov_b32_e32 v30, v29
	v_mov_b64_e32 v[32:33], v[28:29]
	s_and_saveexec_b64 s[8:9], s[44:45]
	s_xor_b64 s[8:9], exec, s[8:9]
	v_mov_b32_e32 v30, v29
	v_mov_b64_e32 v[32:33], v[28:29]
	s_andn2_saveexec_b64 s[8:9], s[8:9]
	s_cbranch_execz .LBB0_193
	v_lshl_or_b32 v66, s28, 7, v65
	v_ashrrev_i32_e32 v67, 31, v66
	v_lshlrev_b64 v[66:67], 2, v[66:67]
	v_lshl_add_u64 v[68:69], v[4:5], 0, v[66:67]
	v_mov_b32_e32 v66, v108
	v_mov_b32_e32 v67, v109
	v_pk_mul_f32 v[66:67], v[30:31], v[66:67] op_sel_hi:[0,1]
	global_store_dwordx2 v[68:69], v[8:9], off
	v_pk_fma_f32 v[8:9], v[8:9], v[28:29], v[66:67] op_sel_hi:[1,0,1]
.LBB0_193:
	s_or_b64 exec, exec, s[8:9]
	v_mov_b32_e32 v33, v28
	v_mov_b32_e32 v31, v29
	s_waitcnt vmcnt(33)
	v_lshlrev_b32_e32 v28, 16, v16
	v_and_b32_e32 v29, 0xffff0000, v16
	v_pk_mul_f32 v[28:29], v[30:31], v[28:29]
	s_or_b32 s28, s48, 15
	v_pk_fma_f32 v[10:11], v[10:11], v[32:33], v[28:29]
	s_waitcnt vmcnt(32)
	v_and_b32_e32 v28, 0xffff0000, v18
	v_lshlrev_b32_e32 v29, 16, v18
	s_lshl_b64 s[8:9], s[28:29], 16
	s_waitcnt lgkmcnt(0)
	v_pk_fma_f32 v[20:21], v[20:21], v[22:23], v[28:29] op_sel_hi:[1,0,1]
	v_lshl_add_u64 v[22:23], v[0:1], 0, s[8:9]
	v_cvt_pk_bf16_f32 v28, v10, v11
	global_store_dword v[22:23], v28, off
	v_mov_b32_e32 v22, s10
	ds_read2_b32 v[28:29], v22 offset0:15 offset1:47
	ds_read_b32 v22, v22 offset:316
	s_lshl_b64 s[8:9], s[28:29], 14
	v_lshl_add_u64 v[30:31], v[2:3], 0, s[8:9]
	v_cvt_pk_bf16_f32 v23, v21, v20
	global_store_dword v[30:31], v23, off
	s_waitcnt lgkmcnt(1)
	v_mov_b32_e32 v30, v29
	v_mov_b64_e32 v[32:33], v[28:29]
	s_and_saveexec_b64 s[8:9], s[44:45]
	s_xor_b64 s[8:9], exec, s[8:9]
	v_mov_b32_e32 v30, v29
	v_mov_b64_e32 v[32:33], v[28:29]
	s_andn2_saveexec_b64 s[8:9], s[8:9]
	s_cbranch_execz .LBB0_151
	v_lshl_or_b32 v66, s28, 7, v65
	v_ashrrev_i32_e32 v67, 31, v66
	v_lshlrev_b64 v[66:67], 2, v[66:67]
	v_lshl_add_u64 v[68:69], v[4:5], 0, v[66:67]
	v_mov_b32_e32 v66, v110
	v_mov_b32_e32 v67, v111
	v_pk_mul_f32 v[66:67], v[30:31], v[66:67] op_sel_hi:[0,1]
	global_store_dwordx2 v[68:69], v[8:9], off
	v_pk_fma_f32 v[8:9], v[8:9], v[28:29], v[66:67] op_sel_hi:[1,0,1]
	s_branch .LBB0_151
